# post-phase row loads hoisted with their address slices; prep LRU conv taps issue all masked loads before use
# speedup vs baseline: 1.0426x; 1.0179x over previous
; __device__ __forceinline__ unsigned pk2(float lo, float hi) { return f2bf(lo) | (f2bf(hi) << 16); }
; __device__ __forceinline__ f32x4 ld_bf4(const bf16* p) { const u32x2 w = *(const u32x2*)p; return (f32x4){__builtin_bit_cast(float, w.x << 16), __builtin_bit_cast(float, w.x & 0xffff0000u), __builtin_bit_cast(float, w.y << 16), __builtin_bit_cast(float, w.y & 0xffff0000u)}; }
; __device__ __forceinline__ f32x4 conv4(const bf16* __restrict__ U, int row, int col, const float* __restrict__ cw, int C, const float* __restrict__ cb) {
;     int t, len; if (row < MLAT) { t = row & (TL - 1); len = TL; } else { t = (row - MLAT) & (TC - 1); len = TC; }
;     f32x4 acc = *(const f32x4*)cb;
; #pragma unroll
;     for (int j = 0; j < 4; ++j) { const int tt = t + j - 1; if (tt >= 0 && tt < len) { const f32x4 xx = ld_bf4(U + (size_t)(row + j - 1) * NUG + col); const f32x4 w = *(const f32x4*)(cw + j * C); acc += xx * w; } }
;     return acc;
; __device__ __forceinline__ void prep_phase(const Params& P, float* L, int l) {
;     ...
;         for (int i = tid; i < 1024; i += 512) { const int r = i >> 4, c4 = (i & 15) << 2;
;             const f32x4 v = conv4((const bf16*)(P.ws + WS_UG), row0 + r, G_LRU_X + h * 64 + c4, cw + h * 64 + c4, 512, cb + h * 64 + c4);
;             *(f32x4*)&xs[r * 68 + c4] = v; u32x2 w; w.x = pk2(v.x, v.y); w.y = pk2(v.z, v.w); *(u32x2*)&xb[r * 72 + c4] = w; }
.LBB0_270:
	v_and_b32_e32 v14, 60, v12
	v_lshlrev_b32_e32 v2, 2, v14
	global_load_dwordx4 v[4:7], v2, s[26:27]
	v_ashrrev_i32_e32 v15, 4, v13
	v_add_u32_e32 v16, s49, v15
	v_cmp_gt_i32_e32 vcc, s69, v16
	v_mov_b32_e32 v11, 0x7ff
	v_or_b32_e32 v10, s50, v14
	v_cndmask_b32_e32 v11, v186, v11, vcc
	v_and_b32_e32 v18, v11, v16
	v_cndmask_b32_e32 v17, v192, v193, vcc
	v_add_u32_e32 v19, -1, v18
	v_lshlrev_b32_e32 v10, 1, v10
	v_mov_b32_e32 v11, v3
	v_lshl_add_u64 v[8:9], s[24:25], 0, v[2:3]
	v_lshl_add_u64 v[10:11], s[92:93], 0, v[10:11]
	v_add_co_u32_e32 v104, vcc, 0x1000, v8
	s_nop 1
	v_addc_co_u32_e32 v105, vcc, 0, v9, vcc
	v_add_u32_e32 v19, -1, v18
	v_cmp_lt_u32_e32 vcc, v19, v17
	s_and_saveexec_b64 s[30:31], vcc
	v_add_u32_e32 v19, -1, v16
	v_mad_i64_i32 v[20:21], s[52:53], v19, s91, v[10:11]
	global_load_dwordx2 v[80:81], v[20:21], off
	global_load_dwordx4 v[88:91], v[8:9], off
	s_or_b64 exec, exec, s[30:31]
	v_cmp_lt_u32_e32 vcc, v18, v17
	s_and_saveexec_b64 s[30:31], vcc
	v_mad_i64_i32 v[20:21], s[52:53], v16, s91, v[10:11]
	global_load_dwordx2 v[82:83], v[20:21], off
	global_load_dwordx4 v[92:95], v[8:9], off offset:2048
	s_or_b64 exec, exec, s[30:31]
	v_add_u32_e32 v19, 1, v18
	v_cmp_lt_u32_e32 vcc, v19, v17
	s_and_saveexec_b64 s[30:31], vcc
	v_add_u32_e32 v19, 1, v16
	v_mad_i64_i32 v[20:21], s[52:53], v19, s91, v[10:11]
	global_load_dwordx2 v[84:85], v[20:21], off
	global_load_dwordx4 v[96:99], v[104:105], off
	s_or_b64 exec, exec, s[30:31]
	v_add_u32_e32 v19, 2, v18
	v_cmp_lt_u32_e32 vcc, v19, v17
	s_and_saveexec_b64 s[30:31], vcc
	v_add_u32_e32 v19, 2, v16
	v_mad_i64_i32 v[20:21], s[52:53], v19, s91, v[10:11]
	global_load_dwordx2 v[86:87], v[20:21], off
	global_load_dwordx4 v[100:103], v[104:105], off offset:2048
	s_or_b64 exec, exec, s[30:31]
	v_add_u32_e32 v19, -1, v18
	v_cmp_lt_u32_e32 vcc, v19, v17
	s_and_saveexec_b64 s[30:31], vcc
	s_waitcnt vmcnt(6)
	v_lshlrev_b32_e32 v24, 16, v80
	v_and_b32_e32 v25, 0xffff0000, v80
	v_lshlrev_b32_e32 v26, 16, v81
	v_and_b32_e32 v27, 0xffff0000, v81
	v_pk_fma_f32 v[6:7], v[90:91], v[26:27], v[6:7]
	v_pk_fma_f32 v[4:5], v[88:89], v[24:25], v[4:5]
	s_or_b64 exec, exec, s[30:31]
	v_cmp_lt_u32_e32 vcc, v18, v17
	s_and_saveexec_b64 s[30:31], vcc
	s_waitcnt vmcnt(4)
	v_lshlrev_b32_e32 v24, 16, v82
	v_and_b32_e32 v25, 0xffff0000, v82
	v_lshlrev_b32_e32 v26, 16, v83
	v_and_b32_e32 v27, 0xffff0000, v83
	v_pk_fma_f32 v[6:7], v[94:95], v[26:27], v[6:7]
	v_pk_fma_f32 v[4:5], v[92:93], v[24:25], v[4:5]
	s_or_b64 exec, exec, s[30:31]
	v_add_u32_e32 v19, 1, v18
	v_cmp_lt_u32_e32 vcc, v19, v17
	s_and_saveexec_b64 s[30:31], vcc
	s_waitcnt vmcnt(2)
	v_lshlrev_b32_e32 v24, 16, v84
	v_and_b32_e32 v25, 0xffff0000, v84
	v_lshlrev_b32_e32 v26, 16, v85
	v_and_b32_e32 v27, 0xffff0000, v85
	v_pk_fma_f32 v[4:5], v[96:97], v[24:25], v[4:5]
	v_pk_fma_f32 v[6:7], v[98:99], v[26:27], v[6:7]
	s_or_b64 exec, exec, s[30:31]
	v_add_u32_e32 v19, 2, v18
	v_cmp_lt_u32_e32 vcc, v19, v17
	s_and_saveexec_b64 s[30:31], vcc
	s_waitcnt vmcnt(0)
	v_lshlrev_b32_e32 v24, 16, v86
	v_and_b32_e32 v25, 0xffff0000, v86
	v_lshlrev_b32_e32 v26, 16, v87
	v_and_b32_e32 v27, 0xffff0000, v87
	v_pk_fma_f32 v[4:5], v[100:101], v[24:25], v[4:5]
	v_pk_fma_f32 v[6:7], v[102:103], v[26:27], v[6:7]
	s_branch .LBB0_269

; __device__ __forceinline__ float silu_(float x) { return x * sigmoid_(x); }
; __device__ __forceinline__ float gelu_tanh_(float x) { const float z = 0.7978845608f * (x + 0.044715f * x * x * x); const float t = 1.f - 2.f * __builtin_amdgcn_rcpf(1.f + __expf(2.f * z)); return 0.5f * x * (1.f + t); }
; __device__ __forceinline__ unsigned pk2(float lo, float hi) { return f2bf(lo) | (f2bf(hi) << 16); }
; __device__ __forceinline__ float dot4(f32x4 a) { return (a.x * a.x + a.y * a.y) + (a.z * a.z + a.w * a.w); }
; __device__ __forceinline__ f32x4 ld_bf4(const bf16* p) { const u32x2 w = *(const u32x2*)p; return (f32x4){__builtin_bit_cast(float, w.x << 16), __builtin_bit_cast(float, w.x & 0xffff0000u), __builtin_bit_cast(float, w.y << 16), __builtin_bit_cast(float, w.y & 0xffff0000u)}; }
; #define LDY(p) ld_bf4(p)
; __device__ __forceinline__ void post_phase(const Params& P, int l, int mrows) {
;     ...
;         const bf16* ug = (const bf16*)(P.ws + WS_UG) + (size_t)row * NUG; bf16* yc = YC + (size_t)row * DM;
;     ...
;         {
;             f32x4 gg[2]; float ss = 0.f;
; #pragma unroll
;             for (int j = 0; j < 2; ++j) { const int c = 4 * lane + 256 * j; const float dsk = P.ssd_d[l * 8 + (c >> 6)]; const f32x4 y = LDY(YDP(0, 0) + c) + LDY(YDP(0, 1) + c) + ld_bf4((const bf16*)(P.ws + WS_XBC) + (size_t)row * 768 + c) * dsk; const f32x4 z = ld_bf4(ug + G_SSD_Z + c);
;                 f32x4 t; t.x = y.x * silu_(z.x); t.y = y.y * silu_(z.y); t.z = y.z * silu_(z.z); t.w = y.w * silu_(z.w); gg[j] = t; ss += dot4(t); }
;             const float rs = rsqrtf(wave_sum(ss) * (1.f / 512.f) + EPS);
; #pragma unroll
;             for (int j = 0; j < 2; ++j) { const int c = 4 * lane + 256 * j; const f32x4 w = *(const f32x4*)(P.ssd_norm_w + (size_t)l * 512 + c); const f32x4 o = gg[j] * rs * w;
;                 u32x2 pk; pk.x = pk2(o.x, o.y); pk.y = pk2(o.z, o.w); *(u32x2*)(yc + c) = pk; }
;         }
;         {
; #pragma unroll
;             for (int j = 0; j < 2; ++j) { const int c = 4 * lane + 256 * j; const f32x4 hh = LDY(YDP(1, 0) + c) + LDY(YDP(1, 1) + c); const f32x4 gb = ld_bf4(ug + G_LRU_G + c);
;                 f32x4 o; o.x = hh.x * gelu_tanh_(gb.x); o.y = hh.y * gelu_tanh_(gb.y); o.z = hh.z * gelu_tanh_(gb.z); o.w = hh.w * gelu_tanh_(gb.w);
.LBB0_341:
	v_lshl_add_u64 v[48:49], s[10:11], 0, v[2:3]
	v_add_co_u32_e32 v50, vcc, 0x34f00000, v48
	s_mov_b32 s5, 0x2ec00000
	s_nop 0
	v_addc_co_u32_e32 v51, vcc, 0, v49, vcc
	v_add_co_u32_e32 v52, vcc, 0x35800000, v48
	global_load_dwordx2 v[54:55], v[50:51], off
	s_nop 0
	v_addc_co_u32_e32 v53, vcc, 0, v49, vcc
	global_load_dwordx2 v[56:57], v[52:53], off
	global_load_dword v58, v[0:1], off
	v_lshl_add_u64 v[60:61], s[8:9], 0, v[2:3]
	v_add_co_u32_e32 v62, vcc, s5, v60
	s_nop 1
	v_addc_co_u32_e32 v63, vcc, 0, v61, vcc
	global_load_dwordx2 v[64:65], v[62:63], off
	s_mov_b32 s5, 0x26200000
	v_lshl_add_u64 v[66:67], s[18:19], 0, v[2:3]
	v_add_co_u32_e32 v68, vcc, s5, v66
	s_mov_b32 s5, 0x36100000
	s_nop 0
	v_addc_co_u32_e32 v69, vcc, 0, v67, vcc
	global_load_dwordx2 v[70:71], v[68:69], off
	global_load_dword v72, v[4:5], off
	global_load_dwordx2 v[74:75], v[50:51], off offset:512
	global_load_dwordx2 v[76:77], v[52:53], off offset:512
	global_load_dwordx2 v[78:79], v[62:63], off offset:512
	global_load_dwordx2 v[80:81], v[68:69], off offset:512
	global_load_dwordx4 v[82:85], v[6:7], off
	global_load_dwordx4 v[86:89], v[6:7], off offset:1024
	v_add_co_u32_e32 v90, vcc, s5, v48
	s_mov_b32 s5, 0x36a00000
	s_nop 0
	v_addc_co_u32_e32 v91, vcc, 0, v49, vcc
	v_add_co_u32_e32 v92, vcc, s5, v48
	global_load_dwordx2 v[94:95], v[90:91], off
	s_nop 0
	v_addc_co_u32_e32 v93, vcc, 0, v49, vcc
	global_load_dwordx2 v[96:97], v[92:93], off
	s_mov_b32 s5, 0x37300000
	global_load_dwordx2 v[98:99], v[68:69], off offset:1024
	global_load_dwordx2 v[100:101], v[90:91], off offset:512
	global_load_dwordx2 v[102:103], v[92:93], off offset:512
	global_load_dwordx2 v[104:105], v[68:69], off offset:1536
	v_add_co_u32_e32 v106, vcc, s5, v48
	s_mov_b32 s5, 0x37c00000
	s_nop 0
	v_addc_co_u32_e32 v107, vcc, 0, v49, vcc
	v_add_co_u32_e32 v108, vcc, s5, v48
	global_load_dwordx2 v[110:111], v[106:107], off
	s_nop 0
	v_addc_co_u32_e32 v109, vcc, 0, v49, vcc
	global_load_dwordx2 v[112:113], v[108:109], off
	s_mov_b32 s5, 0x38500000
	global_load_dwordx4 v[114:117], v[8:9], off
	global_load_dwordx2 v[118:119], v[68:69], off offset:2048
	global_load_dwordx2 v[120:121], v[106:107], off offset:512
	global_load_dwordx2 v[122:123], v[108:109], off offset:512
	global_load_dwordx4 v[124:127], v[8:9], off
	global_load_dwordx2 v[128:129], v[68:69], off offset:2560
	v_add_co_u32_e32 v130, vcc, s5, v48
	s_mov_b32 s5, 0x38e00000
	s_nop 0
	v_addc_co_u32_e32 v131, vcc, 0, v49, vcc
	v_add_co_u32_e32 v136, vcc, s5, v48
	global_load_dwordx2 v[138:139], v[130:131], off
	s_nop 0
	v_addc_co_u32_e32 v137, vcc, 0, v49, vcc
	global_load_dwordx2 v[140:141], v[136:137], off
	global_load_dwordx2 v[142:143], v[130:131], off offset:512
	global_load_dwordx2 v[144:145], v[136:137], off offset:512
	global_load_dwordx2 v[146:147], v[68:69], off offset:3072
	global_load_dwordx2 v[148:149], v[68:69], off offset:3584
	s_nop 0
	s_nop 0
	s_mov_b32 s6, 0x358637bd
	s_add_i32 s0, s0, s4
	s_waitcnt vmcnt(31)
	v_lshlrev_b32_e32 v14, 16, v54
	v_and_b32_e32 v15, 0xffff0000, v54
	v_lshlrev_b32_e32 v12, 16, v55
	v_and_b32_e32 v13, 0xffff0000, v55
	s_waitcnt vmcnt(30)
	v_lshlrev_b32_e32 v24, 16, v56
	v_and_b32_e32 v25, 0xffff0000, v56
	v_lshlrev_b32_e32 v22, 16, v57
	v_and_b32_e32 v23, 0xffff0000, v57
	v_pk_add_f32 v[12:13], v[12:13], v[22:23]
	v_pk_add_f32 v[14:15], v[14:15], v[24:25]
	s_nop 0
	s_add_u32 s8, s8, s20
	s_waitcnt vmcnt(28)
	v_lshlrev_b32_e32 v26, 16, v64
	v_and_b32_e32 v27, 0xffff0000, v64
	v_lshlrev_b32_e32 v24, 16, v65
	v_and_b32_e32 v25, 0xffff0000, v65
	v_mov_b32_e32 v59, v11
	v_pk_fma_f32 v[24:25], v[58:59], v[24:25], v[12:13] op_sel_hi:[0,1,1]
	v_mov_b32_e32 v59, v11
	v_pk_fma_f32 v[12:13], v[58:59], v[26:27], v[14:15] op_sel_hi:[0,1,1]
	s_nop 0
	s_waitcnt vmcnt(27)
	v_lshlrev_b32_e32 v26, 16, v70
	v_and_b32_e32 v27, 0xffff0000, v70
	v_mul_f32_e32 v14, 0xbfb8aa3b, v26
	v_exp_f32_e32 v14, v14
	s_nop 0
	v_add_f32_e32 v14, 1.0, v14
	v_rcp_f32_e32 v28, v14
	v_mul_f32_e32 v14, 0xbfb8aa3b, v27
	v_exp_f32_e32 v14, v14
	s_nop 0
	v_add_f32_e32 v14, 1.0, v14
	v_rcp_f32_e32 v29, v14
	v_lshlrev_b32_e32 v14, 16, v71
	v_and_b32_e32 v15, 0xffff0000, v71
	v_pk_mul_f32 v[26:27], v[28:29], v[26:27]
	s_nop 0
	v_pk_mul_f32 v[12:13], v[26:27], v[12:13]
	v_mul_f32_e32 v26, 0xbfb8aa3b, v14
	v_mul_f32_e32 v27, 0xbfb8aa3b, v15
	v_exp_f32_e32 v26, v26
	v_exp_f32_e32 v27, v27
	v_add_f32_e32 v26, 1.0, v26
	v_add_f32_e32 v27, 1.0, v27
	v_rcp_f32_e32 v26, v26
	v_rcp_f32_e32 v27, v27
	s_nop 0
	v_pk_mul_f32 v[14:15], v[26:27], v[14:15]
	s_nop 0
	v_pk_mul_f32 v[14:15], v[14:15], v[24:25]
	s_nop 0
	s_waitcnt vmcnt(25)
	v_lshlrev_b32_e32 v26, 16, v74
	v_and_b32_e32 v27, 0xffff0000, v74
	v_lshlrev_b32_e32 v18, 16, v75
	v_and_b32_e32 v19, 0xffff0000, v75
	s_waitcnt vmcnt(24)
	v_lshlrev_b32_e32 v28, 16, v76
	v_and_b32_e32 v29, 0xffff0000, v76
	v_lshlrev_b32_e32 v20, 16, v77
	v_and_b32_e32 v21, 0xffff0000, v77
	v_pk_add_f32 v[18:19], v[18:19], v[20:21]
	v_pk_add_f32 v[26:27], v[26:27], v[28:29]
	s_waitcnt vmcnt(23)
	v_lshlrev_b32_e32 v22, 16, v78
	v_and_b32_e32 v23, 0xffff0000, v78
	v_lshlrev_b32_e32 v20, 16, v79
	v_and_b32_e32 v21, 0xffff0000, v79
	v_mov_b32_e32 v73, v25
	v_pk_fma_f32 v[20:21], v[72:73], v[20:21], v[18:19] op_sel_hi:[0,1,1]
	v_mov_b32_e32 v73, v25
	v_pk_fma_f32 v[18:19], v[72:73], v[22:23], v[26:27] op_sel_hi:[0,1,1]
	s_waitcnt vmcnt(22)
; __device__ __forceinline__ float silu_(float x) { return x * sigmoid_(x); }
; __device__ __forceinline__ float gelu_tanh_(float x) { const float z = 0.7978845608f * (x + 0.044715f * x * x * x); const float t = 1.f - 2.f * __builtin_amdgcn_rcpf(1.f + __expf(2.f * z)); return 0.5f * x * (1.f + t); }
; __device__ __forceinline__ unsigned pk2(float lo, float hi) { return f2bf(lo) | (f2bf(hi) << 16); }
; __device__ __forceinline__ float dot4(f32x4 a) { return (a.x * a.x + a.y * a.y) + (a.z * a.z + a.w * a.w); }
; __device__ __forceinline__ f32x4 ld_bf4(const bf16* p) { const u32x2 w = *(const u32x2*)p; return (f32x4){__builtin_bit_cast(float, w.x << 16), __builtin_bit_cast(float, w.x & 0xffff0000u), __builtin_bit_cast(float, w.y << 16), __builtin_bit_cast(float, w.y & 0xffff0000u)}; }
; #define LDY(p) ld_bf4(p)
; __device__ __forceinline__ void post_phase(const Params& P, int l, int mrows) {
;     ...
;             for (int j = 0; j < 2; ++j) { const int c = 4 * lane + 256 * j; const float dsk = P.ssd_d[l * 8 + (c >> 6)]; const f32x4 y = LDY(YDP(0, 0) + c) + LDY(YDP(0, 1) + c) + ld_bf4((const bf16*)(P.ws + WS_XBC) + (size_t)row * 768 + c) * dsk; const f32x4 z = ld_bf4(ug + G_SSD_Z + c);
;                 f32x4 t; t.x = y.x * silu_(z.x); t.y = y.y * silu_(z.y); t.z = y.z * silu_(z.z); t.w = y.w * silu_(z.w); gg[j] = t; ss += dot4(t); }
;             const float rs = rsqrtf(wave_sum(ss) * (1.f / 512.f) + EPS);
; #pragma unroll
;             for (int j = 0; j < 2; ++j) { const int c = 4 * lane + 256 * j; const f32x4 w = *(const f32x4*)(P.ssd_norm_w + (size_t)l * 512 + c); const f32x4 o = gg[j] * rs * w;
;                 u32x2 pk; pk.x = pk2(o.x, o.y); pk.y = pk2(o.z, o.w); *(u32x2*)(yc + c) = pk; }
;         }
;         {
; #pragma unroll
;             for (int j = 0; j < 2; ++j) { const int c = 4 * lane + 256 * j; const f32x4 hh = LDY(YDP(1, 0) + c) + LDY(YDP(1, 1) + c); const f32x4 gb = ld_bf4(ug + G_LRU_G + c);
;                 f32x4 o; o.x = hh.x * gelu_tanh_(gb.x); o.y = hh.y * gelu_tanh_(gb.y); o.z = hh.z * gelu_tanh_(gb.z); o.w = hh.w * gelu_tanh_(gb.w);
;                 u32x2 pk; pk.x = pk2(o.x, o.y); pk.y = pk2(o.z, o.w); *(u32x2*)(yc + 512 + c) = pk; }
	v_lshlrev_b32_e32 v24, 16, v80
	v_and_b32_e32 v25, 0xffff0000, v80
	v_mul_f32_e32 v22, 0xbfb8aa3b, v24
	v_exp_f32_e32 v22, v22
	s_nop 0
	v_add_f32_e32 v22, 1.0, v22
	v_rcp_f32_e32 v26, v22
	v_mul_f32_e32 v22, 0xbfb8aa3b, v25
	v_exp_f32_e32 v22, v22
	s_nop 0
	v_add_f32_e32 v22, 1.0, v22
	v_rcp_f32_e32 v27, v22
	v_lshlrev_b32_e32 v22, 16, v81
	v_and_b32_e32 v23, 0xffff0000, v81
	v_pk_mul_f32 v[24:25], v[26:27], v[24:25]
	s_nop 0
	v_pk_mul_f32 v[18:19], v[24:25], v[18:19]
	v_mul_f32_e32 v24, 0xbfb8aa3b, v22
	v_mul_f32_e32 v25, 0xbfb8aa3b, v23
	v_exp_f32_e32 v24, v24
	v_exp_f32_e32 v25, v25
	v_mov_b32_e32 v26, v15
	v_add_f32_e32 v24, 1.0, v24
	v_add_f32_e32 v25, 1.0, v25
	v_rcp_f32_e32 v24, v24
	v_rcp_f32_e32 v25, v25
	s_nop 0
	v_pk_mul_f32 v[22:23], v[24:25], v[22:23]
	s_nop 0
	v_pk_mul_f32 v[20:21], v[22:23], v[20:21]
	v_mov_b32_e32 v24, v13
	v_mov_b32_e32 v25, v19
	v_mov_b32_e32 v22, v12
	v_mov_b32_e32 v23, v18
	v_pk_mul_f32 v[24:25], v[24:25], v[24:25]
	v_mov_b32_e32 v27, v21
	v_pk_fma_f32 v[22:23], v[22:23], v[22:23], v[24:25]
	v_mov_b32_e32 v24, v14
	v_mov_b32_e32 v25, v20
	v_pk_mul_f32 v[26:27], v[26:27], v[26:27]
	s_nop 0
	v_pk_fma_f32 v[24:25], v[24:25], v[24:25], v[26:27]
	s_nop 0
	v_pk_add_f32 v[22:23], v[22:23], v[24:25]
	v_add_f32_e32 v22, v22, v23
	ds_bpermute_b32 v23, v30, v22
	s_waitcnt lgkmcnt(0)
	v_add_f32_e32 v22, v22, v23
	ds_bpermute_b32 v23, v31, v22
	s_waitcnt lgkmcnt(0)
	v_add_f32_e32 v22, v22, v23
	ds_bpermute_b32 v23, v32, v22
	s_waitcnt lgkmcnt(0)
	v_add_f32_e32 v22, v22, v23
	ds_bpermute_b32 v23, v33, v22
	s_waitcnt lgkmcnt(0)
	v_add_f32_e32 v22, v22, v23
	ds_bpermute_b32 v23, v34, v22
	s_waitcnt lgkmcnt(0)
	v_add_f32_e32 v22, v22, v23
	ds_bpermute_b32 v23, v35, v22
	s_waitcnt lgkmcnt(0)
	v_add_f32_e32 v22, v22, v23
	v_fmamk_f32 v22, v22, 0x3b000000, v169
	v_cmp_gt_f32_e32 vcc, s3, v22
	v_mul_f32_e32 v23, 0x4b800000, v22
	s_nop 0
	v_cndmask_b32_e32 v22, v22, v23, vcc
	v_rsq_f32_e32 v22, v22
	s_nop 0
	v_mul_f32_e32 v23, 0x45800000, v22
	v_cndmask_b32_e32 v22, v22, v23, vcc
	v_pk_mul_f32 v[12:13], v[12:13], v[22:23] op_sel_hi:[1,0]
	v_pk_mul_f32 v[14:15], v[14:15], v[22:23] op_sel_hi:[1,0]
	s_waitcnt vmcnt(21)
	v_pk_mul_f32 v[12:13], v[82:83], v[12:13]
	s_nop 0
	v_bfe_u32 v23, v12, 16, 1
	v_add3_u32 v12, v12, v23, s71
	v_bfe_u32 v23, v13, 16, 1
	v_pk_mul_f32 v[14:15], v[84:85], v[14:15]
	v_lshrrev_b32_e32 v12, 16, v12
	v_add3_u32 v13, v13, v23, s71
	v_and_or_b32 v24, v13, s70, v12
	v_bfe_u32 v12, v14, 16, 1
	v_add3_u32 v12, v14, v12, s71
	v_bfe_u32 v13, v15, 16, 1
	v_lshrrev_b32_e32 v12, 16, v12
	v_add3_u32 v13, v15, v13, s71
	v_and_or_b32 v25, v13, s70, v12
	v_lshl_add_u64 v[12:13], s[14:15], 0, v[2:3]
	v_add_co_u32_e32 v12, vcc, s22, v12
	v_pk_mul_f32 v[14:15], v[18:19], v[22:23] op_sel_hi:[1,0]
	s_nop 0
	v_addc_co_u32_e32 v13, vcc, 0, v13, vcc
	global_store_dwordx2 v[12:13], v[24:25], off
	v_pk_mul_f32 v[18:19], v[20:21], v[22:23] op_sel_hi:[1,0]
	s_waitcnt vmcnt(21)
	v_pk_mul_f32 v[14:15], v[86:87], v[14:15]
	s_nop 0
	v_bfe_u32 v20, v14, 16, 1
	v_add3_u32 v14, v14, v20, s71
	v_bfe_u32 v20, v15, 16, 1
	v_pk_mul_f32 v[18:19], v[88:89], v[18:19]
	v_lshrrev_b32_e32 v14, 16, v14
	v_add3_u32 v15, v15, v20, s71
	v_and_or_b32 v14, v15, s70, v14
	v_bfe_u32 v15, v18, 16, 1
	v_add3_u32 v15, v18, v15, s71
	v_bfe_u32 v18, v19, 16, 1
	v_lshrrev_b32_e32 v15, 16, v15
	v_add3_u32 v18, v19, v18, s71
	v_and_or_b32 v15, v18, s70, v15
	global_store_dwordx2 v[12:13], v[14:15], off offset:512
	s_nop 0
	s_nop 0
	s_waitcnt vmcnt(21)
	v_lshlrev_b32_e32 v20, 16, v94
	v_and_b32_e32 v21, 0xffff0000, v94
	v_lshlrev_b32_e32 v18, 16, v95
	v_and_b32_e32 v19, 0xffff0000, v95
	s_waitcnt vmcnt(20)
	v_lshlrev_b32_e32 v26, 16, v96
	v_and_b32_e32 v27, 0xffff0000, v96
	v_lshlrev_b32_e32 v24, 16, v97
	v_and_b32_e32 v25, 0xffff0000, v97
	v_pk_add_f32 v[18:19], v[18:19], v[24:25]
	v_pk_add_f32 v[20:21], v[20:21], v[26:27]
	s_waitcnt vmcnt(19)
	v_lshlrev_b32_e32 v26, 16, v98
	v_mul_f32_e32 v28, 0x3d372713, v26
	v_mul_f32_e32 v28, v28, v26
	v_mov_b32_e32 v29, v26
	v_and_b32_e32 v24, 0xffff0000, v98
	v_fmac_f32_e32 v29, v28, v29
	v_mul_f32_e32 v28, 0x3f4c422a, v29
	v_mul_f32_e32 v29, 0x3d372713, v24
	v_mul_f32_e32 v29, v29, v24
	v_mov_b32_e32 v36, v24
	v_fmac_f32_e32 v36, v29, v36
	v_mul_f32_e32 v29, 0x3f4c422a, v36
	v_add_f32_e32 v29, v29, v29
	v_mul_f32_e32 v29, 0x3fb8aa3b, v29
	v_exp_f32_e32 v29, v29
	v_lshlrev_b32_e32 v27, 16, v99
	v_mov_b32_e32 v37, v27
	v_add_f32_e32 v28, v28, v28
	v_add_f32_e32 v29, 1.0, v29
	v_rcp_f32_e32 v36, v29
	v_mul_f32_e32 v29, 0x3d372713, v27
	v_mul_f32_e32 v29, v29, v27
	v_fmac_f32_e32 v37, v29, v37
	v_mul_f32_e32 v29, 0x3f4c422a, v37
	v_add_f32_e32 v29, v29, v29
	v_mul_f32_e32 v28, 0x3fb8aa3b, v28
	v_mul_f32_e32 v29, 0x3fb8aa3b, v29
	v_exp_f32_e32 v28, v28
	v_exp_f32_e32 v29, v29
	v_and_b32_e32 v25, 0xffff0000, v99
	v_pk_mul_f32 v[26:27], v[26:27], 0.5 op_sel_hi:[1,0]
	v_add_f32_e32 v28, 1.0, v28
	v_add_f32_e32 v29, 1.0, v29
	v_rcp_f32_e32 v28, v28
	v_rcp_f32_e32 v29, v29
	s_nop 0
	v_pk_fma_f32 v[28:29], v[28:29], 2.0, 1.0 op_sel_hi:[1,0,0] neg_lo:[1,0,0] neg_hi:[1,0,0]
	s_nop 0
	v_pk_add_f32 v[28:29], v[28:29], 1.0 op_sel_hi:[1,0]
	s_nop 0
	v_pk_mul_f32 v[26:27], v[26:27], v[28:29]
	v_mov_b32_e32 v29, v18
	v_mul_f32_e32 v18, 0x3d372713, v25
	v_mov_b32_e32 v28, v20
	v_mul_f32_e32 v18, v18, v25
	v_mov_b32_e32 v20, v25
	v_fmac_f32_e32 v20, v18, v20
	v_mul_f32_e32 v18, 0x3f4c422a, v20
	v_add_f32_e32 v18, v18, v18
	v_mul_f32_e32 v18, 0x3fb8aa3b, v18
	v_exp_f32_e32 v18, v18
	v_pk_mul_f32 v[26:27], v[28:29], v[26:27]
	v_pk_mul_f32 v[24:25], v[24:25], 0.5 op_sel_hi:[1,0]
	v_and_b32_sdwa v20, v27, v173 dst_sel:DWORD dst_unused:UNUSED_PAD src0_sel:WORD_1 src1_sel:DWORD
	v_add_f32_e32 v18, 1.0, v18
	v_rcp_f32_e32 v37, v18
	v_mov_b32_e32 v18, v21
	v_and_b32_sdwa v21, v26, v173 dst_sel:DWORD dst_unused:UNUSED_PAD src0_sel:WORD_1 src1_sel:DWORD
	v_add3_u32 v21, v26, v21, s71
	v_pk_fma_f32 v[28:29], v[36:37], 2.0, 1.0 op_sel_hi:[1,0,0] neg_lo:[1,0,0] neg_hi:[1,0,0]
	v_add3_u32 v20, v27, v20, s71
	v_pk_add_f32 v[28:29], v[28:29], 1.0 op_sel_hi:[1,0]
	s_nop 0
	v_pk_mul_f32 v[24:25], v[24:25], v[28:29]
	s_nop 0
	v_pk_mul_f32 v[18:19], v[18:19], v[24:25]
	s_nop 0
	v_and_b32_sdwa v24, v19, v173 dst_sel:DWORD dst_unused:UNUSED_PAD src0_sel:WORD_1 src1_sel:DWORD
	v_and_b32_sdwa v25, v18, v173 dst_sel:DWORD dst_unused:UNUSED_PAD src0_sel:WORD_1 src1_sel:DWORD
	v_add3_u32 v19, v19, v24, s71
	v_add3_u32 v18, v18, v25, s71
	v_and_b32_e32 v19, 0xffff0000, v19
	v_and_b32_e32 v18, 0xffff0000, v18
	v_or_b32_sdwa v19, v19, v20 dst_sel:DWORD dst_unused:UNUSED_PAD src0_sel:DWORD src1_sel:WORD_1
	v_or_b32_sdwa v18, v18, v21 dst_sel:DWORD dst_unused:UNUSED_PAD src0_sel:DWORD src1_sel:WORD_1
	global_store_dwordx2 v[12:13], v[18:19], off offset:1024
	s_nop 0
	s_waitcnt vmcnt(19)
; __device__ __forceinline__ float silu_(float x) { return x * sigmoid_(x); }
; __device__ __forceinline__ float gelu_tanh_(float x) { const float z = 0.7978845608f * (x + 0.044715f * x * x * x); const float t = 1.f - 2.f * __builtin_amdgcn_rcpf(1.f + __expf(2.f * z)); return 0.5f * x * (1.f + t); }
; __device__ __forceinline__ unsigned pk2(float lo, float hi) { return f2bf(lo) | (f2bf(hi) << 16); }
; __device__ __forceinline__ float dot4(f32x4 a) { return (a.x * a.x + a.y * a.y) + (a.z * a.z + a.w * a.w); }
; __device__ __forceinline__ f32x4 ld_bf4(const bf16* p) { const u32x2 w = *(const u32x2*)p; return (f32x4){__builtin_bit_cast(float, w.x << 16), __builtin_bit_cast(float, w.x & 0xffff0000u), __builtin_bit_cast(float, w.y << 16), __builtin_bit_cast(float, w.y & 0xffff0000u)}; }
; #define LDY(p) ld_bf4(p)
; __device__ __forceinline__ void post_phase(const Params& P, int l, int mrows) {
;     ...
;         {
; #pragma unroll
;             for (int j = 0; j < 2; ++j) { const int c = 4 * lane + 256 * j; const f32x4 hh = LDY(YDP(1, 0) + c) + LDY(YDP(1, 1) + c); const f32x4 gb = ld_bf4(ug + G_LRU_G + c);
;                 f32x4 o; o.x = hh.x * gelu_tanh_(gb.x); o.y = hh.y * gelu_tanh_(gb.y); o.z = hh.z * gelu_tanh_(gb.z); o.w = hh.w * gelu_tanh_(gb.w);
;                 u32x2 pk; pk.x = pk2(o.x, o.y); pk.y = pk2(o.z, o.w); *(u32x2*)(yc + 512 + c) = pk; }
;         }
;         {
; #pragma unroll
;             for (int j = 0; j < 2; ++j) { const int c = 4 * lane + 256 * j; const f32x4 o = LDY(YDP(2, 0) + c) + LDY(YDP(2, 1) + c);
;                 const float rs = rsqrtf(half_sum(dot4(o)) * (1.f / 128.f) + EPS); const f32x4 w = *(const f32x4*)(P.hgrn_norm_w + (size_t)l * 128 + (c & 127)); const f32x4 gt = ld_bf4(ug + G_HG_G + c);
;                 f32x4 r; r.x = o.x * rs * w.x * silu_(gt.x); r.y = o.y * rs * w.y * silu_(gt.y); r.z = o.z * rs * w.z * silu_(gt.z); r.w = o.w * rs * w.w * silu_(gt.w);
;                 u32x2 pk; pk.x = pk2(r.x, r.y); pk.y = pk2(r.z, r.w); *(u32x2*)(yc + 1024 + c) = pk; }
	v_lshlrev_b32_e32 v18, 16, v100
	v_and_b32_e32 v19, 0xffff0000, v100
	v_lshlrev_b32_e32 v14, 16, v101
	v_and_b32_e32 v15, 0xffff0000, v101
	s_waitcnt vmcnt(18)
	v_lshlrev_b32_e32 v22, 16, v102
	v_and_b32_e32 v23, 0xffff0000, v102
	v_lshlrev_b32_e32 v20, 16, v103
	v_and_b32_e32 v21, 0xffff0000, v103
	v_pk_add_f32 v[14:15], v[14:15], v[20:21]
	v_pk_add_f32 v[18:19], v[18:19], v[22:23]
	s_waitcnt vmcnt(17)
	v_lshlrev_b32_e32 v22, 16, v104
	v_mul_f32_e32 v24, 0x3d372713, v22
	v_mul_f32_e32 v24, v24, v22
	v_mov_b32_e32 v25, v22
	v_and_b32_e32 v20, 0xffff0000, v104
	v_fmac_f32_e32 v25, v24, v25
	v_mul_f32_e32 v24, 0x3f4c422a, v25
	v_mul_f32_e32 v25, 0x3d372713, v20
	v_mul_f32_e32 v25, v25, v20
	v_mov_b32_e32 v26, v20
	v_fmac_f32_e32 v26, v25, v26
	v_mul_f32_e32 v25, 0x3f4c422a, v26
	v_add_f32_e32 v25, v25, v25
	v_mul_f32_e32 v25, 0x3fb8aa3b, v25
	v_exp_f32_e32 v25, v25
	v_lshlrev_b32_e32 v23, 16, v105
	v_mov_b32_e32 v27, v23
	v_add_f32_e32 v24, v24, v24
	v_add_f32_e32 v25, 1.0, v25
	v_rcp_f32_e32 v26, v25
	v_mul_f32_e32 v25, 0x3d372713, v23
	v_mul_f32_e32 v25, v25, v23
	v_fmac_f32_e32 v27, v25, v27
	v_mul_f32_e32 v25, 0x3f4c422a, v27
	v_add_f32_e32 v25, v25, v25
	v_mul_f32_e32 v24, 0x3fb8aa3b, v24
	v_mul_f32_e32 v25, 0x3fb8aa3b, v25
	v_exp_f32_e32 v24, v24
	v_exp_f32_e32 v25, v25
	v_and_b32_e32 v21, 0xffff0000, v105
	v_pk_mul_f32 v[22:23], v[22:23], 0.5 op_sel_hi:[1,0]
	v_add_f32_e32 v24, 1.0, v24
	v_add_f32_e32 v25, 1.0, v25
	v_rcp_f32_e32 v24, v24
	v_rcp_f32_e32 v25, v25
	s_nop 0
	v_pk_fma_f32 v[24:25], v[24:25], 2.0, 1.0 op_sel_hi:[1,0,0] neg_lo:[1,0,0] neg_hi:[1,0,0]
	s_nop 0
	v_pk_add_f32 v[24:25], v[24:25], 1.0 op_sel_hi:[1,0]
	s_nop 0
	v_pk_mul_f32 v[22:23], v[22:23], v[24:25]
	v_mov_b32_e32 v25, v14
	v_mul_f32_e32 v14, 0x3d372713, v21
	v_mov_b32_e32 v24, v18
	v_mul_f32_e32 v14, v14, v21
	v_mov_b32_e32 v18, v21
	v_fmac_f32_e32 v18, v14, v18
	v_mul_f32_e32 v14, 0x3f4c422a, v18
	v_add_f32_e32 v14, v14, v14
	v_mul_f32_e32 v14, 0x3fb8aa3b, v14
	v_exp_f32_e32 v14, v14
	v_pk_mul_f32 v[22:23], v[24:25], v[22:23]
	v_pk_mul_f32 v[20:21], v[20:21], 0.5 op_sel_hi:[1,0]
	v_and_b32_sdwa v18, v23, v173 dst_sel:DWORD dst_unused:UNUSED_PAD src0_sel:WORD_1 src1_sel:DWORD
	v_add_f32_e32 v14, 1.0, v14
	v_rcp_f32_e32 v27, v14
	v_mov_b32_e32 v14, v19
	v_and_b32_sdwa v19, v22, v173 dst_sel:DWORD dst_unused:UNUSED_PAD src0_sel:WORD_1 src1_sel:DWORD
	v_add3_u32 v19, v22, v19, s71
	v_pk_fma_f32 v[24:25], v[26:27], 2.0, 1.0 op_sel_hi:[1,0,0] neg_lo:[1,0,0] neg_hi:[1,0,0]
	v_add3_u32 v18, v23, v18, s71
	v_pk_add_f32 v[24:25], v[24:25], 1.0 op_sel_hi:[1,0]
	s_nop 0
	v_pk_mul_f32 v[20:21], v[20:21], v[24:25]
	s_nop 0
	v_pk_mul_f32 v[14:15], v[14:15], v[20:21]
	s_nop 0
	v_and_b32_sdwa v20, v15, v173 dst_sel:DWORD dst_unused:UNUSED_PAD src0_sel:WORD_1 src1_sel:DWORD
	v_and_b32_sdwa v21, v14, v173 dst_sel:DWORD dst_unused:UNUSED_PAD src0_sel:WORD_1 src1_sel:DWORD
	v_add3_u32 v15, v15, v20, s71
	v_add3_u32 v14, v14, v21, s71
	v_and_b32_e32 v15, 0xffff0000, v15
	v_and_b32_e32 v14, 0xffff0000, v14
	v_or_b32_sdwa v15, v15, v18 dst_sel:DWORD dst_unused:UNUSED_PAD src0_sel:DWORD src1_sel:WORD_1
	v_or_b32_sdwa v14, v14, v19 dst_sel:DWORD dst_unused:UNUSED_PAD src0_sel:DWORD src1_sel:WORD_1
	global_store_dwordx2 v[12:13], v[14:15], off offset:1536
	s_nop 0
	s_nop 0
	s_waitcnt vmcnt(17)
	v_lshlrev_b32_e32 v20, 16, v110
	v_and_b32_e32 v21, 0xffff0000, v110
	v_lshlrev_b32_e32 v18, 16, v111
	v_and_b32_e32 v19, 0xffff0000, v111
	s_waitcnt vmcnt(16)
	v_lshlrev_b32_e32 v26, 16, v112
	v_and_b32_e32 v27, 0xffff0000, v112
	v_lshlrev_b32_e32 v24, 16, v113
	v_and_b32_e32 v25, 0xffff0000, v113
	v_pk_add_f32 v[26:27], v[20:21], v[26:27]
	v_pk_add_f32 v[24:25], v[18:19], v[24:25]
	v_pk_mul_f32 v[20:21], v[26:27], v[26:27]
	v_pk_mul_f32 v[18:19], v[24:25], v[24:25]
	v_mov_b32_e32 v44, v26
	v_pk_mov_b32 v[28:29], v[20:21], v[18:19] op_sel:[1,0]
	v_mov_b32_e32 v21, v19
	v_pk_add_f32 v[28:29], v[28:29], v[20:21]
	v_mov_b32_e32 v45, v24
	v_mov_b32_e32 v24, v27
	s_waitcnt vmcnt(15)
	v_mov_b32_e32 v46, v114
	s_waitcnt vmcnt(14)
	v_lshlrev_b32_e32 v39, 16, v119
	v_lshlrev_b32_e32 v38, 16, v118
	v_and_b32_e32 v36, 0xffff0000, v118
	v_mul_f32_e32 v41, 0xbfb8aa3b, v36
	v_mul_f32_e32 v18, 0xbfb8aa3b, v39
	v_exp_f32_e32 v41, v41
	v_exp_f32_e32 v18, v18
	v_and_b32_e32 v37, 0xffff0000, v119
	v_mul_f32_e32 v40, 0xbfb8aa3b, v38
	v_add_f32_e32 v41, 1.0, v41
	v_add_f32_e32 v18, 1.0, v18
	v_rcp_f32_e32 v42, v41
	v_rcp_f32_e32 v41, v18
	v_mul_f32_e32 v18, 0xbfb8aa3b, v37
	v_exp_f32_e32 v18, v18
	v_exp_f32_e32 v40, v40
	v_mov_b32_e32 v47, v116
	v_mov_b32_e32 v20, v115
	v_add_f32_e32 v18, 1.0, v18
	v_rcp_f32_e32 v43, v18
	v_add_f32_e32 v40, 1.0, v40
	v_rcp_f32_e32 v40, v40
	s_waitcnt vmcnt(13)
	v_lshlrev_b32_e32 v26, 16, v120
	v_pk_mul_f32 v[18:19], v[42:43], v[36:37]
	v_and_b32_e32 v27, 0xffff0000, v120
	v_lshlrev_b32_e32 v14, 16, v121
	v_and_b32_e32 v15, 0xffff0000, v121
	s_waitcnt vmcnt(12)
	v_lshlrev_b32_e32 v36, 16, v122
	v_and_b32_e32 v37, 0xffff0000, v122
	v_lshlrev_b32_e32 v22, 16, v123
	v_and_b32_e32 v23, 0xffff0000, v123
	v_pk_add_f32 v[26:27], v[26:27], v[36:37]
	v_pk_add_f32 v[22:23], v[14:15], v[22:23]
	v_pk_mul_f32 v[36:37], v[26:27], v[26:27]
	v_pk_mul_f32 v[14:15], v[22:23], v[22:23]
	v_pk_mul_f32 v[38:39], v[40:41], v[38:39]
	v_pk_mov_b32 v[40:41], v[36:37], v[14:15] op_sel:[1,0]
	v_mov_b32_e32 v37, v15
	v_pk_add_f32 v[14:15], v[40:41], v[36:37]
	v_mov_b32_e32 v37, v28
	v_mov_b32_e32 v36, v14
	v_mov_b32_e32 v28, v15
	v_pk_add_f32 v[14:15], v[36:37], v[28:29]
	ds_bpermute_b32 v29, v30, v15
	ds_bpermute_b32 v28, v30, v14
	v_mov_b32_e32 v43, v22
	v_mov_b32_e32 v22, v27
	v_mov_b32_e32 v42, v26
	s_waitcnt lgkmcnt(0)
; __device__ __forceinline__ float silu_(float x) { return x * sigmoid_(x); }
; __device__ __forceinline__ unsigned pk2(float lo, float hi) { return f2bf(lo) | (f2bf(hi) << 16); }
; __device__ __forceinline__ float dot4(f32x4 a) { return (a.x * a.x + a.y * a.y) + (a.z * a.z + a.w * a.w); }
; __device__ __forceinline__ f32x4 ld_bf4(const bf16* p) { const u32x2 w = *(const u32x2*)p; return (f32x4){__builtin_bit_cast(float, w.x << 16), __builtin_bit_cast(float, w.x & 0xffff0000u), __builtin_bit_cast(float, w.y << 16), __builtin_bit_cast(float, w.y & 0xffff0000u)}; }
; #define LDY(p) ld_bf4(p)
; __device__ __forceinline__ void post_phase(const Params& P, int l, int mrows) {
;     ...
;         {
; #pragma unroll
;             for (int j = 0; j < 2; ++j) { const int c = 4 * lane + 256 * j; const f32x4 o = LDY(YDP(2, 0) + c) + LDY(YDP(2, 1) + c);
;                 const float rs = rsqrtf(half_sum(dot4(o)) * (1.f / 128.f) + EPS); const f32x4 w = *(const f32x4*)(P.hgrn_norm_w + (size_t)l * 128 + (c & 127)); const f32x4 gt = ld_bf4(ug + G_HG_G + c);
;                 f32x4 r; r.x = o.x * rs * w.x * silu_(gt.x); r.y = o.y * rs * w.y * silu_(gt.y); r.z = o.z * rs * w.z * silu_(gt.z); r.w = o.w * rs * w.w * silu_(gt.w);
;                 u32x2 pk; pk.x = pk2(r.x, r.y); pk.y = pk2(r.z, r.w); *(u32x2*)(yc + 1024 + c) = pk; }
;         }
;         {
; #pragma unroll
;             for (int j = 0; j < 2; ++j) { const int c = 4 * lane + 256 * j; const f32x4 o = LDY(YDP(3, 0) + c) + LDY(YDP(3, 1) + c);
;                 const float rs = rsqrtf(half_sum(dot4(o)) * (1.f / 128.f) + EPS); const f32x4 gt = ld_bf4(ug + G_RT_G + c);
;                 f32x4 r; r.x = o.x * rs * silu_(gt.x); r.y = o.y * rs * silu_(gt.y); r.z = o.z * rs * silu_(gt.z); r.w = o.w * rs * silu_(gt.w);
;                 u32x2 pk; pk.x = pk2(r.x, r.y); pk.y = pk2(r.z, r.w); *(u32x2*)(yc + 1536 + c) = pk; }
	v_pk_add_f32 v[14:15], v[14:15], v[28:29]
	ds_bpermute_b32 v29, v31, v15
	ds_bpermute_b32 v28, v31, v14
	s_waitcnt lgkmcnt(0)
	v_pk_add_f32 v[14:15], v[14:15], v[28:29]
	ds_bpermute_b32 v29, v32, v15
	ds_bpermute_b32 v28, v32, v14
	s_waitcnt lgkmcnt(0)
	v_pk_add_f32 v[14:15], v[14:15], v[28:29]
	ds_bpermute_b32 v29, v33, v15
	ds_bpermute_b32 v28, v33, v14
	s_waitcnt lgkmcnt(0)
	v_pk_add_f32 v[14:15], v[14:15], v[28:29]
	ds_bpermute_b32 v29, v34, v15
	ds_bpermute_b32 v28, v34, v14
	s_waitcnt lgkmcnt(0)
	v_pk_add_f32 v[28:29], v[14:15], v[28:29]
	v_mov_b64_e32 v[14:15], s[6:7]
	v_pk_fma_f32 v[28:29], v[28:29], s[24:25], v[14:15] op_sel_hi:[1,0,0]
	s_nop 0
	v_mul_f32_e32 v36, 0x4b800000, v29
	v_cmp_gt_f32_e64 s[6:7], s3, v29
	v_cmp_gt_f32_e32 vcc, s3, v28
	s_nop 0
	v_cndmask_b32_e64 v29, v29, v36, s[6:7]
	v_rsq_f32_e32 v29, v29
	s_nop 0
	v_mul_f32_e32 v36, 0x45800000, v29
	v_cndmask_b32_e64 v36, v29, v36, s[6:7]
	v_pk_mul_f32 v[24:25], v[24:25], v[36:37] op_sel_hi:[1,0]
	v_pk_mul_f32 v[40:41], v[44:45], v[36:37] op_sel_hi:[1,0]
	v_mov_b32_e32 v21, v117
	v_pk_mul_f32 v[20:21], v[20:21], v[24:25]
	v_pk_mul_f32 v[40:41], v[46:47], v[40:41]
	v_pk_mul_f32 v[18:19], v[18:19], v[20:21]
	v_pk_mul_f32 v[38:39], v[38:39], v[40:41]
	v_and_b32_sdwa v24, v19, v173 dst_sel:DWORD dst_unused:UNUSED_PAD src0_sel:WORD_1 src1_sel:DWORD
	v_and_b32_sdwa v25, v18, v173 dst_sel:DWORD dst_unused:UNUSED_PAD src0_sel:WORD_1 src1_sel:DWORD
	v_and_b32_sdwa v20, v39, v173 dst_sel:DWORD dst_unused:UNUSED_PAD src0_sel:WORD_1 src1_sel:DWORD
	v_and_b32_sdwa v21, v38, v173 dst_sel:DWORD dst_unused:UNUSED_PAD src0_sel:WORD_1 src1_sel:DWORD
	v_add3_u32 v19, v19, v24, s71
	v_add3_u32 v18, v18, v25, s71
	v_add3_u32 v21, v38, v21, s71
	v_add3_u32 v20, v39, v20, s71
	v_and_b32_e32 v19, 0xffff0000, v19
	v_and_b32_e32 v18, 0xffff0000, v18
	v_or_b32_sdwa v19, v19, v20 dst_sel:DWORD dst_unused:UNUSED_PAD src0_sel:DWORD src1_sel:WORD_1
	v_or_b32_sdwa v18, v18, v21 dst_sel:DWORD dst_unused:UNUSED_PAD src0_sel:DWORD src1_sel:WORD_1
	global_store_dwordx2 v[12:13], v[18:19], off offset:2048
	v_mul_f32_e32 v18, 0x4b800000, v28
	v_cndmask_b32_e32 v18, v28, v18, vcc
	v_rsq_f32_e32 v18, v18
	s_nop 0
	v_mul_f32_e32 v19, 0x45800000, v18
	v_cndmask_b32_e32 v24, v18, v19, vcc
	s_waitcnt vmcnt(12)
	v_mov_b32_e32 v44, v124
	s_waitcnt vmcnt(11)
	v_lshlrev_b32_e32 v36, 16, v128
	v_mul_f32_e32 v25, 0xbfb8aa3b, v36
	v_exp_f32_e32 v25, v25
	v_and_b32_e32 v28, 0xffff0000, v128
	v_lshlrev_b32_e32 v37, 16, v129
	v_mul_f32_e32 v18, 0xbfb8aa3b, v37
	v_add_f32_e32 v25, 1.0, v25
	v_rcp_f32_e32 v38, v25
	v_mul_f32_e32 v25, 0xbfb8aa3b, v28
	v_exp_f32_e32 v25, v25
	v_exp_f32_e32 v18, v18
	v_and_b32_e32 v29, 0xffff0000, v129
	v_mov_b32_e32 v45, v126
	v_add_f32_e32 v25, 1.0, v25
	v_add_f32_e32 v18, 1.0, v18
	v_pk_mul_f32 v[22:23], v[22:23], v[24:25] op_sel_hi:[1,0]
	v_mov_b32_e32 v20, v125
	v_rcp_f32_e32 v39, v18
	v_mov_b32_e32 v21, v127
	v_pk_mul_f32 v[18:19], v[20:21], v[22:23]
	v_mul_f32_e32 v20, 0xbfb8aa3b, v29
	v_exp_f32_e32 v20, v20
	v_rcp_f32_e32 v40, v25
	v_pk_mul_f32 v[42:43], v[42:43], v[24:25] op_sel_hi:[1,0]
	v_pk_mul_f32 v[36:37], v[38:39], v[36:37]
	v_add_f32_e32 v20, 1.0, v20
	v_rcp_f32_e32 v41, v20
	v_pk_mul_f32 v[42:43], v[44:45], v[42:43]
	v_pk_mul_f32 v[20:21], v[40:41], v[28:29]
	s_nop 0
	v_pk_mul_f32 v[18:19], v[20:21], v[18:19]
	v_pk_mul_f32 v[36:37], v[36:37], v[42:43]
	v_and_b32_sdwa v22, v19, v173 dst_sel:DWORD dst_unused:UNUSED_PAD src0_sel:WORD_1 src1_sel:DWORD
	v_and_b32_sdwa v23, v18, v173 dst_sel:DWORD dst_unused:UNUSED_PAD src0_sel:WORD_1 src1_sel:DWORD
	v_and_b32_sdwa v20, v37, v173 dst_sel:DWORD dst_unused:UNUSED_PAD src0_sel:WORD_1 src1_sel:DWORD
	v_and_b32_sdwa v21, v36, v173 dst_sel:DWORD dst_unused:UNUSED_PAD src0_sel:WORD_1 src1_sel:DWORD
	v_add3_u32 v19, v19, v22, s71
	v_add3_u32 v18, v18, v23, s71
	v_add3_u32 v21, v36, v21, s71
	v_add3_u32 v20, v37, v20, s71
	v_and_b32_e32 v19, 0xffff0000, v19
	v_and_b32_e32 v18, 0xffff0000, v18
	v_or_b32_sdwa v19, v19, v20 dst_sel:DWORD dst_unused:UNUSED_PAD src0_sel:DWORD src1_sel:WORD_1
	v_or_b32_sdwa v18, v18, v21 dst_sel:DWORD dst_unused:UNUSED_PAD src0_sel:DWORD src1_sel:WORD_1
	global_store_dwordx2 v[12:13], v[18:19], off offset:2560
	s_nop 0
	s_nop 0
	s_mul_hi_i32 s5, s4, 0x600
	s_addc_u32 s9, s9, s5
	s_add_u32 s10, s10, s12
	s_addc_u32 s11, s11, s13
	s_add_u32 s14, s14, s16
	s_addc_u32 s15, s15, s17
	s_add_u32 s18, s18, s1
	s_mul_hi_i32 s5, s4, 0x2a00
	s_addc_u32 s19, s19, s5
	s_cmp_ge_i32 s0, s23
	s_waitcnt vmcnt(11)
	v_lshlrev_b32_e32 v20, 16, v138
	v_and_b32_e32 v21, 0xffff0000, v138
	v_lshlrev_b32_e32 v22, 16, v139
	v_and_b32_e32 v23, 0xffff0000, v139
	s_waitcnt vmcnt(10)
	v_lshlrev_b32_e32 v26, 16, v140
	v_and_b32_e32 v27, 0xffff0000, v140
	v_lshlrev_b32_e32 v24, 16, v141
	v_and_b32_e32 v25, 0xffff0000, v141
	v_pk_add_f32 v[26:27], v[20:21], v[26:27]
	v_pk_add_f32 v[20:21], v[22:23], v[24:25]
	v_pk_mul_f32 v[24:25], v[26:27], v[26:27]
	v_pk_mul_f32 v[22:23], v[20:21], v[20:21]
	s_nop 0
	v_pk_mov_b32 v[28:29], v[24:25], v[22:23] op_sel:[1,0]
	v_mov_b32_e32 v25, v23
	v_pk_add_f32 v[22:23], v[28:29], v[24:25]
	s_waitcnt vmcnt(7)
; __device__ __forceinline__ float silu_(float x) { return x * sigmoid_(x); }
; __device__ __forceinline__ unsigned pk2(float lo, float hi) { return f2bf(lo) | (f2bf(hi) << 16); }
; __device__ __forceinline__ float dot4(f32x4 a) { return (a.x * a.x + a.y * a.y) + (a.z * a.z + a.w * a.w); }
; __device__ __forceinline__ f32x4 ld_bf4(const bf16* p) { const u32x2 w = *(const u32x2*)p; return (f32x4){__builtin_bit_cast(float, w.x << 16), __builtin_bit_cast(float, w.x & 0xffff0000u), __builtin_bit_cast(float, w.y << 16), __builtin_bit_cast(float, w.y & 0xffff0000u)}; }
; #define LDY(p) ld_bf4(p)
; __device__ __forceinline__ void post_phase(const Params& P, int l, int mrows) {
;     ...
;         {
; #pragma unroll
;             for (int j = 0; j < 2; ++j) { const int c = 4 * lane + 256 * j; const f32x4 o = LDY(YDP(3, 0) + c) + LDY(YDP(3, 1) + c);
;                 const float rs = rsqrtf(half_sum(dot4(o)) * (1.f / 128.f) + EPS); const f32x4 gt = ld_bf4(ug + G_RT_G + c);
;                 f32x4 r; r.x = o.x * rs * silu_(gt.x); r.y = o.y * rs * silu_(gt.y); r.z = o.z * rs * silu_(gt.z); r.w = o.w * rs * silu_(gt.w);
;                 u32x2 pk; pk.x = pk2(r.x, r.y); pk.y = pk2(r.z, r.w); *(u32x2*)(yc + 1536 + c) = pk; }
;         }
;     ...
;     }
	v_lshlrev_b32_e32 v28, 16, v146
	v_and_b32_e32 v36, 0xffff0000, v146
	v_mul_f32_e32 v24, 0xbfb8aa3b, v28
	v_exp_f32_e32 v24, v24
	v_lshlrev_b32_e32 v29, 16, v147
	v_and_b32_e32 v37, 0xffff0000, v147
	v_mov_b32_e32 v25, v20
	v_add_f32_e32 v24, 1.0, v24
	v_rcp_f32_e32 v38, v24
	v_mul_f32_e32 v24, 0xbfb8aa3b, v36
	v_exp_f32_e32 v24, v24
	v_mul_f32_e32 v20, 0xbfb8aa3b, v29
	v_exp_f32_e32 v20, v20
	v_add_f32_e32 v24, 1.0, v24
	v_rcp_f32_e32 v40, v24
	v_mov_b32_e32 v24, v26
	v_mul_f32_e32 v26, 0xbfb8aa3b, v37
	v_exp_f32_e32 v26, v26
	v_add_f32_e32 v20, 1.0, v20
	v_rcp_f32_e32 v39, v20
	v_mov_b32_e32 v20, v27
	v_add_f32_e32 v26, 1.0, v26
	v_rcp_f32_e32 v41, v26
	v_pk_mul_f32 v[28:29], v[38:39], v[28:29]
	v_lshlrev_b32_e32 v38, 16, v144
	v_and_b32_e32 v39, 0xffff0000, v144
	v_pk_mul_f32 v[26:27], v[40:41], v[36:37]
	v_lshlrev_b32_e32 v36, 16, v142
	v_and_b32_e32 v37, 0xffff0000, v142
	v_lshlrev_b32_e32 v18, 16, v143
	v_and_b32_e32 v19, 0xffff0000, v143
	v_lshlrev_b32_e32 v16, 16, v145
	v_and_b32_e32 v17, 0xffff0000, v145
	v_pk_add_f32 v[36:37], v[36:37], v[38:39]
	v_pk_add_f32 v[16:17], v[18:19], v[16:17]
	v_pk_mul_f32 v[38:39], v[36:37], v[36:37]
	v_pk_mul_f32 v[18:19], v[16:17], v[16:17]
	s_nop 0
	v_pk_mov_b32 v[40:41], v[38:39], v[18:19] op_sel:[1,0]
	v_mov_b32_e32 v39, v19
	v_pk_add_f32 v[18:19], v[40:41], v[38:39]
	v_mov_b32_e32 v39, v22
	v_mov_b32_e32 v38, v18
	v_mov_b32_e32 v22, v19
	v_pk_add_f32 v[18:19], v[38:39], v[22:23]
	ds_bpermute_b32 v23, v30, v19
	ds_bpermute_b32 v22, v30, v18
	s_waitcnt lgkmcnt(0)
	v_pk_add_f32 v[18:19], v[18:19], v[22:23]
	ds_bpermute_b32 v23, v31, v19
	ds_bpermute_b32 v22, v31, v18
	s_waitcnt lgkmcnt(0)
	v_pk_add_f32 v[18:19], v[18:19], v[22:23]
	ds_bpermute_b32 v23, v32, v19
	ds_bpermute_b32 v22, v32, v18
	s_waitcnt lgkmcnt(0)
	v_pk_add_f32 v[18:19], v[18:19], v[22:23]
	ds_bpermute_b32 v23, v33, v19
	ds_bpermute_b32 v22, v33, v18
	s_waitcnt lgkmcnt(0)
	v_pk_add_f32 v[18:19], v[18:19], v[22:23]
	ds_bpermute_b32 v23, v34, v19
	ds_bpermute_b32 v22, v34, v18
	s_waitcnt lgkmcnt(0)
	v_pk_add_f32 v[18:19], v[18:19], v[22:23]
	s_nop 0
	v_pk_fma_f32 v[14:15], v[18:19], s[24:25], v[14:15] op_sel_hi:[1,0,0]
	s_nop 0
	v_mul_f32_e32 v18, 0x4b800000, v15
	v_cmp_gt_f32_e64 s[6:7], s3, v15
	v_cmp_gt_f32_e32 vcc, s3, v14
	s_nop 0
	v_cndmask_b32_e64 v15, v15, v18, s[6:7]
	v_rsq_f32_e32 v15, v15
	s_nop 0
	v_mul_f32_e32 v18, 0x45800000, v15
	v_cndmask_b32_e64 v18, v15, v18, s[6:7]
	v_pk_mul_f32 v[22:23], v[24:25], v[18:19] op_sel_hi:[1,0]
	v_pk_mul_f32 v[18:19], v[20:21], v[18:19] op_sel_hi:[1,0]
	v_pk_mul_f32 v[22:23], v[28:29], v[22:23]
	v_pk_mul_f32 v[18:19], v[26:27], v[18:19]
	v_and_b32_sdwa v20, v22, v173 dst_sel:DWORD dst_unused:UNUSED_PAD src0_sel:WORD_1 src1_sel:DWORD
	v_add3_u32 v20, v22, v20, s71
	v_and_b32_sdwa v21, v19, v173 dst_sel:DWORD dst_unused:UNUSED_PAD src0_sel:WORD_1 src1_sel:DWORD
	v_and_b32_sdwa v22, v18, v173 dst_sel:DWORD dst_unused:UNUSED_PAD src0_sel:WORD_1 src1_sel:DWORD
	v_and_b32_sdwa v15, v23, v173 dst_sel:DWORD dst_unused:UNUSED_PAD src0_sel:WORD_1 src1_sel:DWORD
	v_add3_u32 v19, v19, v21, s71
	v_add3_u32 v18, v18, v22, s71
	v_add3_u32 v15, v23, v15, s71
	v_and_b32_e32 v19, 0xffff0000, v19
	v_and_b32_e32 v18, 0xffff0000, v18
	v_or_b32_sdwa v19, v19, v15 dst_sel:DWORD dst_unused:UNUSED_PAD src0_sel:DWORD src1_sel:WORD_1
	v_or_b32_sdwa v18, v18, v20 dst_sel:DWORD dst_unused:UNUSED_PAD src0_sel:DWORD src1_sel:WORD_1
	global_store_dwordx2 v[12:13], v[18:19], off offset:3072
	v_mul_f32_e32 v15, 0x4b800000, v14
	v_cndmask_b32_e32 v14, v14, v15, vcc
	v_rsq_f32_e32 v14, v14
	v_mov_b32_e32 v24, v36
	v_mov_b32_e32 v25, v16
	v_mov_b32_e32 v16, v37
	v_mul_f32_e32 v15, 0x45800000, v14
	v_cndmask_b32_e32 v14, v14, v15, vcc
	s_waitcnt vmcnt(7)
	v_lshlrev_b32_e32 v18, 16, v148
	v_mul_f32_e32 v15, 0xbfb8aa3b, v18
	v_exp_f32_e32 v15, v15
	v_and_b32_e32 v10, 0xffff0000, v148
	v_lshlrev_b32_e32 v19, 16, v149
	v_and_b32_e32 v11, 0xffff0000, v149
	v_add_f32_e32 v15, 1.0, v15
	v_rcp_f32_e32 v20, v15
	v_mul_f32_e32 v15, 0xbfb8aa3b, v10
	v_exp_f32_e32 v15, v15
	s_nop 0
	v_add_f32_e32 v15, 1.0, v15
	v_rcp_f32_e32 v22, v15
	v_pk_mul_f32 v[24:25], v[24:25], v[14:15] op_sel_hi:[1,0]
	v_mul_f32_e32 v15, 0xbfb8aa3b, v19
	v_exp_f32_e32 v15, v15
	s_nop 0
	v_add_f32_e32 v15, 1.0, v15
	v_rcp_f32_e32 v21, v15
	v_pk_mul_f32 v[14:15], v[16:17], v[14:15] op_sel_hi:[1,0]
	v_mul_f32_e32 v16, 0xbfb8aa3b, v11
	v_exp_f32_e32 v16, v16
	v_pk_mul_f32 v[18:19], v[20:21], v[18:19]
	v_add_f32_e32 v16, 1.0, v16
	v_rcp_f32_e32 v23, v16
	v_pk_mul_f32 v[18:19], v[18:19], v[24:25]
	v_pk_mul_f32 v[10:11], v[22:23], v[10:11]
	s_nop 0
	v_pk_mul_f32 v[10:11], v[10:11], v[14:15]
	v_and_b32_sdwa v14, v19, v173 dst_sel:DWORD dst_unused:UNUSED_PAD src0_sel:WORD_1 src1_sel:DWORD
	v_and_b32_sdwa v16, v11, v173 dst_sel:DWORD dst_unused:UNUSED_PAD src0_sel:WORD_1 src1_sel:DWORD
	v_and_b32_sdwa v17, v10, v173 dst_sel:DWORD dst_unused:UNUSED_PAD src0_sel:WORD_1 src1_sel:DWORD
	v_and_b32_sdwa v15, v18, v173 dst_sel:DWORD dst_unused:UNUSED_PAD src0_sel:WORD_1 src1_sel:DWORD
	v_add3_u32 v11, v11, v16, s71
	v_add3_u32 v10, v10, v17, s71
	v_add3_u32 v15, v18, v15, s71
	v_add3_u32 v14, v19, v14, s71
	v_and_b32_e32 v11, 0xffff0000, v11
	v_and_b32_e32 v10, 0xffff0000, v10
	v_or_b32_sdwa v11, v11, v14 dst_sel:DWORD dst_unused:UNUSED_PAD src0_sel:DWORD src1_sel:WORD_1
	v_or_b32_sdwa v10, v10, v15 dst_sel:DWORD dst_unused:UNUSED_PAD src0_sel:DWORD src1_sel:WORD_1
	global_store_dwordx2 v[12:13], v[10:11], off offset:3584
	s_cbranch_scc0 .LBB0_341
